# mode6: LDS atomic returns pipelined two slots deep
# baseline (speedup 1.0000x reference)
;     ...
; #pragma unroll 1
;     for (int it = 0; it < nit; ++it) {
;         const int kt = kt0 + 4 * (it >> 1), kb = it & 1;
;         const int itn = it + 1 < nit ? it + 1 : it;
;         const bf16_t* np = ikp + (size_t)(256 * (itn >> 1) + 32 * (itn & 1)) * NZ; const bf16x8 n0 = *(const bf16x8*)np, n1 = *(const bf16x8*)(np + 16);
;         f32x2v sc2[8];
; #pragma unroll
;         for (int r = 0; r < 8; ++r) sc2[r] = (f32x2v){0.f, 0.f};
;     ...
;         { f32x16 zero16;
; #pragma unroll
;           for (int r = 0; r < 16; ++r) zero16[r] = 0.f;
;           f32x16 dA0, dA1, dB0, dB1; float wA0, wA1, wB0, wB1;
;           SW_MF(0, dA0, dA1, wA0, wA1);
;           SW_MF(1, dB0, dB1, wB0, wB1); __builtin_amdgcn_sched_barrier(0);
;           SW_VA(dA0, dA1, wA0, wA1);    __builtin_amdgcn_sched_barrier(0);
;           SW_MF(2, dA0, dA1, wA0, wA1); __builtin_amdgcn_sched_barrier(0);
;           SW_VA(dB0, dB1, wB0, wB1);    __builtin_amdgcn_sched_barrier(0);
;           SW_MF(3, dB0, dB1, wB0, wB1); __builtin_amdgcn_sched_barrier(0);
;           SW_VA(dA0, dA1, wA0, wA1);    __builtin_amdgcn_sched_barrier(0);
;           SW_VA(dB0, dB1, wB0, wB1); }
.Lm6_loop:
	s_add_i32 s1, s18, 1
	s_cmp_lt_u32 s1, s25
	s_cselect_b32 s3, s1, s18
	s_lshl_b32 vcc_lo, s3, 7
	s_and_b32 vcc_lo, vcc_lo, 0x7fffff00
	s_lshl_b32 s3, s3, 5
	s_and_b32 s3, s3, 32
	s_or_b32 s3, vcc_lo, s3
	s_lshr_b32 s0, s18, 1
	s_lshl_b32 s0, s0, 2
	s_add_i32 s0, s0, s24
	s_lshl_b32 s0, s0, 6
	s_and_b32 s2, s18, 1
	s_lshl_b32 s2, s2, 5
	s_or_b32 s0, s0, s2
	ds_read_b128 v[0:3], v165
	ds_read_b128 v[4:7], v165 offset:32
	ds_read_b128 v[8:11], v165 offset:64
	ds_read_b128 v[12:15], v165 offset:96
	ds_read2st64_b32 v[80:81], v167 offset1:1
	ds_read2st64_b32 v[82:83], v167 offset0:2 offset1:3
	ds_read2st64_b32 v[84:85], v167 offset0:4 offset1:5
	ds_read2st64_b32 v[86:87], v167 offset0:6 offset1:7
	v_mad_u64_u32 v[114:115], vcc, s3, v223, v[140:141]
	v_or_b32_e32 v124, s0, v159
	global_load_dwordx4 v[64:67], v[114:115], off
	global_load_dwordx4 v[68:71], v[114:115], off offset:32
	s_waitcnt vmcnt(2) lgkmcnt(6)
	v_mfma_f32_32x32x16_bf16 v[16:31], v[132:135], v[0:3], 0
	v_mfma_f32_32x32x16_bf16 v[16:31], v[128:131], v[4:7], v[16:31]
	ds_read_b128 v[0:3], v165 offset:128
	ds_read_b128 v[4:7], v165 offset:160
	s_waitcnt lgkmcnt(6)
	v_mfma_f32_32x32x16_bf16 v[32:47], v[132:135], v[8:11], 0
	v_mfma_f32_32x32x16_bf16 v[32:47], v[128:131], v[12:15], v[32:47]
	ds_read_b128 v[8:11], v165 offset:192
	ds_read_b128 v[12:15], v165 offset:224
	s_nop 7
	s_waitcnt lgkmcnt(4)
	v_mov_b32_e32 v104, v81
	v_mov_b32_e32 v106, v83
	v_mov_b32_e32 v108, v85
	v_mov_b32_e32 v110, v87
	v_pk_mul_f32 v[16:17], v[16:17], v[112:113] clamp
	v_pk_mul_f32 v[18:19], v[18:19], v[112:113] clamp
	v_pk_mul_f32 v[20:21], v[20:21], v[112:113] clamp
	v_pk_mul_f32 v[22:23], v[22:23], v[112:113] clamp
	v_pk_mul_f32 v[24:25], v[24:25], v[112:113] clamp
	v_pk_mul_f32 v[26:27], v[26:27], v[112:113] clamp
	v_pk_mul_f32 v[28:29], v[28:29], v[112:113] clamp
	v_pk_mul_f32 v[30:31], v[30:31], v[112:113] clamp
	v_pk_fma_f32 v[88:89], v[16:17], v[80:81], 0 op_sel_hi:[1,0,0]
	v_pk_fma_f32 v[90:91], v[18:19], v[80:81], 0 op_sel_hi:[1,0,0]
	v_pk_fma_f32 v[92:93], v[20:21], v[80:81], 0 op_sel_hi:[1,0,0]
	v_pk_fma_f32 v[94:95], v[22:23], v[80:81], 0 op_sel_hi:[1,0,0]
	v_pk_fma_f32 v[96:97], v[24:25], v[80:81], 0 op_sel_hi:[1,0,0]
	v_pk_fma_f32 v[98:99], v[26:27], v[80:81], 0 op_sel_hi:[1,0,0]
	v_pk_fma_f32 v[100:101], v[28:29], v[80:81], 0 op_sel_hi:[1,0,0]
	v_pk_fma_f32 v[102:103], v[30:31], v[80:81], 0 op_sel_hi:[1,0,0]
	s_waitcnt lgkmcnt(2)
	v_mfma_f32_32x32x16_bf16 v[16:31], v[132:135], v[0:3], 0
	v_mfma_f32_32x32x16_bf16 v[16:31], v[128:131], v[4:7], v[16:31]
	ds_read_b128 v[0:3], v165 offset:256
	ds_read_b128 v[4:7], v165 offset:288
	v_pk_mul_f32 v[32:33], v[32:33], v[112:113] clamp
	v_pk_mul_f32 v[34:35], v[34:35], v[112:113] clamp
	v_pk_mul_f32 v[36:37], v[36:37], v[112:113] clamp
	v_pk_mul_f32 v[38:39], v[38:39], v[112:113] clamp
	v_pk_mul_f32 v[40:41], v[40:41], v[112:113] clamp
	v_pk_mul_f32 v[42:43], v[42:43], v[112:113] clamp
	v_pk_mul_f32 v[44:45], v[44:45], v[112:113] clamp
	v_pk_mul_f32 v[46:47], v[46:47], v[112:113] clamp
	v_pk_fma_f32 v[88:89], v[32:33], v[104:105], v[88:89] op_sel_hi:[1,0,1]
	v_pk_fma_f32 v[90:91], v[34:35], v[104:105], v[90:91] op_sel_hi:[1,0,1]
	v_pk_fma_f32 v[92:93], v[36:37], v[104:105], v[92:93] op_sel_hi:[1,0,1]
	v_pk_fma_f32 v[94:95], v[38:39], v[104:105], v[94:95] op_sel_hi:[1,0,1]
	v_pk_fma_f32 v[96:97], v[40:41], v[104:105], v[96:97] op_sel_hi:[1,0,1]
	v_pk_fma_f32 v[98:99], v[42:43], v[104:105], v[98:99] op_sel_hi:[1,0,1]
	v_pk_fma_f32 v[100:101], v[44:45], v[104:105], v[100:101] op_sel_hi:[1,0,1]
	v_pk_fma_f32 v[102:103], v[46:47], v[104:105], v[102:103] op_sel_hi:[1,0,1]
	s_waitcnt lgkmcnt(2)
	v_mfma_f32_32x32x16_bf16 v[32:47], v[132:135], v[8:11], 0
	v_mfma_f32_32x32x16_bf16 v[32:47], v[128:131], v[12:15], v[32:47]
	ds_read_b128 v[8:11], v165 offset:320
	ds_read_b128 v[12:15], v165 offset:352
	v_pk_mul_f32 v[16:17], v[16:17], v[112:113] clamp
	v_pk_mul_f32 v[18:19], v[18:19], v[112:113] clamp
	v_pk_mul_f32 v[20:21], v[20:21], v[112:113] clamp
	v_pk_mul_f32 v[22:23], v[22:23], v[112:113] clamp
	v_pk_mul_f32 v[24:25], v[24:25], v[112:113] clamp
	v_pk_mul_f32 v[26:27], v[26:27], v[112:113] clamp
	v_pk_mul_f32 v[28:29], v[28:29], v[112:113] clamp
	v_pk_mul_f32 v[30:31], v[30:31], v[112:113] clamp
	v_pk_fma_f32 v[88:89], v[16:17], v[82:83], v[88:89] op_sel_hi:[1,0,1]
	v_pk_fma_f32 v[90:91], v[18:19], v[82:83], v[90:91] op_sel_hi:[1,0,1]
	v_pk_fma_f32 v[92:93], v[20:21], v[82:83], v[92:93] op_sel_hi:[1,0,1]
	v_pk_fma_f32 v[94:95], v[22:23], v[82:83], v[94:95] op_sel_hi:[1,0,1]
	v_pk_fma_f32 v[96:97], v[24:25], v[82:83], v[96:97] op_sel_hi:[1,0,1]
	v_pk_fma_f32 v[98:99], v[26:27], v[82:83], v[98:99] op_sel_hi:[1,0,1]
	v_pk_fma_f32 v[100:101], v[28:29], v[82:83], v[100:101] op_sel_hi:[1,0,1]
	v_pk_fma_f32 v[102:103], v[30:31], v[82:83], v[102:103] op_sel_hi:[1,0,1]
	s_waitcnt lgkmcnt(2)
	v_mfma_f32_32x32x16_bf16 v[16:31], v[132:135], v[0:3], 0
	v_mfma_f32_32x32x16_bf16 v[16:31], v[128:131], v[4:7], v[16:31]
	ds_read_b128 v[0:3], v165 offset:384
	ds_read_b128 v[4:7], v165 offset:416
	v_pk_mul_f32 v[32:33], v[32:33], v[112:113] clamp
	v_pk_mul_f32 v[34:35], v[34:35], v[112:113] clamp
	v_pk_mul_f32 v[36:37], v[36:37], v[112:113] clamp
	v_pk_mul_f32 v[38:39], v[38:39], v[112:113] clamp
	v_pk_mul_f32 v[40:41], v[40:41], v[112:113] clamp
	v_pk_mul_f32 v[42:43], v[42:43], v[112:113] clamp
	v_pk_mul_f32 v[44:45], v[44:45], v[112:113] clamp
	v_pk_mul_f32 v[46:47], v[46:47], v[112:113] clamp
	v_pk_fma_f32 v[88:89], v[32:33], v[106:107], v[88:89] op_sel_hi:[1,0,1]
	v_pk_fma_f32 v[90:91], v[34:35], v[106:107], v[90:91] op_sel_hi:[1,0,1]
	v_pk_fma_f32 v[92:93], v[36:37], v[106:107], v[92:93] op_sel_hi:[1,0,1]
	v_pk_fma_f32 v[94:95], v[38:39], v[106:107], v[94:95] op_sel_hi:[1,0,1]
	v_pk_fma_f32 v[96:97], v[40:41], v[106:107], v[96:97] op_sel_hi:[1,0,1]
	v_pk_fma_f32 v[98:99], v[42:43], v[106:107], v[98:99] op_sel_hi:[1,0,1]
	v_pk_fma_f32 v[100:101], v[44:45], v[106:107], v[100:101] op_sel_hi:[1,0,1]
	v_pk_fma_f32 v[102:103], v[46:47], v[106:107], v[102:103] op_sel_hi:[1,0,1]
	s_waitcnt lgkmcnt(2)
; __device__ __forceinline__ unsigned sortable(float f) { const unsigned u = __float_as_uint(f); return u ^ ((unsigned)((int)u >> 31) | 0x80000000u); }
; __device__ __forceinline__ int bucketf(float f) { const unsigned u = __float_as_uint(f); const int idx = (int)((u >> 20) & 0x7FFu); const int c = min(max(idx - 816, 128), 255); return c ^ (((int)u >> 31) & 255); }
;     ...
;         { f32x16 zero16;
; #pragma unroll
;           for (int r = 0; r < 16; ++r) zero16[r] = 0.f;
;           f32x16 dA0, dA1, dB0, dB1; float wA0, wA1, wB0, wB1;
;           SW_MF(0, dA0, dA1, wA0, wA1);
;           SW_MF(1, dB0, dB1, wB0, wB1); __builtin_amdgcn_sched_barrier(0);
;           SW_VA(dA0, dA1, wA0, wA1);    __builtin_amdgcn_sched_barrier(0);
;           SW_MF(2, dA0, dA1, wA0, wA1); __builtin_amdgcn_sched_barrier(0);
;           SW_VA(dB0, dB1, wB0, wB1);    __builtin_amdgcn_sched_barrier(0);
;           SW_MF(3, dB0, dB1, wB0, wB1); __builtin_amdgcn_sched_barrier(0);
;           SW_VA(dA0, dA1, wA0, wA1);    __builtin_amdgcn_sched_barrier(0);
;           SW_VA(dB0, dB1, wB0, wB1); }
;     ...
;         f32x16 sc;
; #pragma unroll
;         for (int r = 0; r < 16; ++r) sc[r] = sc2[r >> 1][r & 1];
;         const unsigned s0 = (unsigned)(64 * kt + 32 * kb + 4 * hi);
; #pragma unroll
;         for (int r = 0; r < 16; ++r) { const unsigned s = s0 + (unsigned)((r & 3) + 8 * (r >> 2));
;             if (MODE == 5) { __hip_atomic_fetch_add(hist + 64 * bucketf(sc[r]), 1u, __ATOMIC_RELAXED, __HIP_MEMORY_SCOPE_WORKGROUP); continue; }
;             if (MODE == 6) {
;                 if (sc[r] >= t_hi) { const unsigned pos = __hip_atomic_fetch_add(cnt, 1u, __ATOMIC_RELAXED, __HIP_MEMORY_SCOPE_WORKGROUP); sel[pos & 255u] = (unsigned short)s; }
;                 else if (sc[r] >= t_lo) { const unsigned key = (sortable(sc[r]) & 0xFFFFE000u) | (8191u - s);
;                     const unsigned pos = __hip_atomic_fetch_add(ccnt, 1u, __ATOMIC_RELAXED, __HIP_MEMORY_SCOPE_WORKGROUP); cand[pos & (DS_CAP - 1)] = key; }
	v_mfma_f32_32x32x16_bf16 v[32:47], v[132:135], v[8:11], 0
	v_mfma_f32_32x32x16_bf16 v[32:47], v[128:131], v[12:15], v[32:47]
	ds_read_b128 v[8:11], v165 offset:448
	ds_read_b128 v[12:15], v165 offset:480
	v_pk_mul_f32 v[16:17], v[16:17], v[112:113] clamp
	v_pk_mul_f32 v[18:19], v[18:19], v[112:113] clamp
	v_pk_mul_f32 v[20:21], v[20:21], v[112:113] clamp
	v_pk_mul_f32 v[22:23], v[22:23], v[112:113] clamp
	v_pk_mul_f32 v[24:25], v[24:25], v[112:113] clamp
	v_pk_mul_f32 v[26:27], v[26:27], v[112:113] clamp
	v_pk_mul_f32 v[28:29], v[28:29], v[112:113] clamp
	v_pk_mul_f32 v[30:31], v[30:31], v[112:113] clamp
	v_pk_fma_f32 v[88:89], v[16:17], v[84:85], v[88:89] op_sel_hi:[1,0,1]
	v_pk_fma_f32 v[90:91], v[18:19], v[84:85], v[90:91] op_sel_hi:[1,0,1]
	v_pk_fma_f32 v[92:93], v[20:21], v[84:85], v[92:93] op_sel_hi:[1,0,1]
	v_pk_fma_f32 v[94:95], v[22:23], v[84:85], v[94:95] op_sel_hi:[1,0,1]
	v_pk_fma_f32 v[96:97], v[24:25], v[84:85], v[96:97] op_sel_hi:[1,0,1]
	v_pk_fma_f32 v[98:99], v[26:27], v[84:85], v[98:99] op_sel_hi:[1,0,1]
	v_pk_fma_f32 v[100:101], v[28:29], v[84:85], v[100:101] op_sel_hi:[1,0,1]
	v_pk_fma_f32 v[102:103], v[30:31], v[84:85], v[102:103] op_sel_hi:[1,0,1]
	s_waitcnt lgkmcnt(2)
	v_mfma_f32_32x32x16_bf16 v[16:31], v[132:135], v[0:3], 0
	v_mfma_f32_32x32x16_bf16 v[16:31], v[128:131], v[4:7], v[16:31]
	v_pk_mul_f32 v[32:33], v[32:33], v[112:113] clamp
	v_pk_mul_f32 v[34:35], v[34:35], v[112:113] clamp
	v_pk_mul_f32 v[36:37], v[36:37], v[112:113] clamp
	v_pk_mul_f32 v[38:39], v[38:39], v[112:113] clamp
	v_pk_mul_f32 v[40:41], v[40:41], v[112:113] clamp
	v_pk_mul_f32 v[42:43], v[42:43], v[112:113] clamp
	v_pk_mul_f32 v[44:45], v[44:45], v[112:113] clamp
	v_pk_mul_f32 v[46:47], v[46:47], v[112:113] clamp
	v_pk_fma_f32 v[88:89], v[32:33], v[108:109], v[88:89] op_sel_hi:[1,0,1]
	v_pk_fma_f32 v[90:91], v[34:35], v[108:109], v[90:91] op_sel_hi:[1,0,1]
	v_pk_fma_f32 v[92:93], v[36:37], v[108:109], v[92:93] op_sel_hi:[1,0,1]
	v_pk_fma_f32 v[94:95], v[38:39], v[108:109], v[94:95] op_sel_hi:[1,0,1]
	v_pk_fma_f32 v[96:97], v[40:41], v[108:109], v[96:97] op_sel_hi:[1,0,1]
	v_pk_fma_f32 v[98:99], v[42:43], v[108:109], v[98:99] op_sel_hi:[1,0,1]
	v_pk_fma_f32 v[100:101], v[44:45], v[108:109], v[100:101] op_sel_hi:[1,0,1]
	v_pk_fma_f32 v[102:103], v[46:47], v[108:109], v[102:103] op_sel_hi:[1,0,1]
	s_waitcnt lgkmcnt(0)
	v_mfma_f32_32x32x16_bf16 v[32:47], v[132:135], v[8:11], 0
	v_mfma_f32_32x32x16_bf16 v[32:47], v[128:131], v[12:15], v[32:47]
	v_pk_mul_f32 v[16:17], v[16:17], v[112:113] clamp
	v_pk_mul_f32 v[18:19], v[18:19], v[112:113] clamp
	v_pk_mul_f32 v[20:21], v[20:21], v[112:113] clamp
	v_pk_mul_f32 v[22:23], v[22:23], v[112:113] clamp
	v_pk_mul_f32 v[24:25], v[24:25], v[112:113] clamp
	v_pk_mul_f32 v[26:27], v[26:27], v[112:113] clamp
	v_pk_mul_f32 v[28:29], v[28:29], v[112:113] clamp
	v_pk_mul_f32 v[30:31], v[30:31], v[112:113] clamp
	v_pk_fma_f32 v[88:89], v[16:17], v[86:87], v[88:89] op_sel_hi:[1,0,1]
	v_pk_fma_f32 v[90:91], v[18:19], v[86:87], v[90:91] op_sel_hi:[1,0,1]
	v_pk_fma_f32 v[92:93], v[20:21], v[86:87], v[92:93] op_sel_hi:[1,0,1]
	v_pk_fma_f32 v[94:95], v[22:23], v[86:87], v[94:95] op_sel_hi:[1,0,1]
	v_pk_fma_f32 v[96:97], v[24:25], v[86:87], v[96:97] op_sel_hi:[1,0,1]
	v_pk_fma_f32 v[98:99], v[26:27], v[86:87], v[98:99] op_sel_hi:[1,0,1]
	v_pk_fma_f32 v[100:101], v[28:29], v[86:87], v[100:101] op_sel_hi:[1,0,1]
	v_pk_fma_f32 v[102:103], v[30:31], v[86:87], v[102:103] op_sel_hi:[1,0,1]
	v_pk_mul_f32 v[32:33], v[32:33], v[112:113] clamp
	v_pk_mul_f32 v[34:35], v[34:35], v[112:113] clamp
	v_pk_mul_f32 v[36:37], v[36:37], v[112:113] clamp
	v_pk_mul_f32 v[38:39], v[38:39], v[112:113] clamp
	v_pk_mul_f32 v[40:41], v[40:41], v[112:113] clamp
	v_pk_mul_f32 v[42:43], v[42:43], v[112:113] clamp
	v_pk_mul_f32 v[44:45], v[44:45], v[112:113] clamp
	v_pk_mul_f32 v[46:47], v[46:47], v[112:113] clamp
	v_pk_fma_f32 v[88:89], v[32:33], v[110:111], v[88:89] op_sel_hi:[1,0,1]
	v_pk_fma_f32 v[90:91], v[34:35], v[110:111], v[90:91] op_sel_hi:[1,0,1]
	v_pk_fma_f32 v[92:93], v[36:37], v[110:111], v[92:93] op_sel_hi:[1,0,1]
	v_pk_fma_f32 v[94:95], v[38:39], v[110:111], v[94:95] op_sel_hi:[1,0,1]
	v_pk_fma_f32 v[96:97], v[40:41], v[110:111], v[96:97] op_sel_hi:[1,0,1]
	v_pk_fma_f32 v[98:99], v[42:43], v[110:111], v[98:99] op_sel_hi:[1,0,1]
	v_pk_fma_f32 v[100:101], v[44:45], v[110:111], v[100:101] op_sel_hi:[1,0,1]
	v_pk_fma_f32 v[102:103], v[46:47], v[110:111], v[102:103] op_sel_hi:[1,0,1]
	v_cmp_ge_f32_e64 s[40:41], v88, v122
	v_cmp_ge_f32_e64 s[42:43], v88, v123
	v_mov_b32_e32 v18, v124
	s_andn2_b64 s[42:43], s[42:43], s[40:41]
	s_mov_b64 exec, s[40:41]
	ds_add_rtn_u32 v16, v180, v222
	s_mov_b64 exec, s[42:43]
	ds_add_rtn_u32 v16, v171, v222
	s_mov_b64 exec, -1
	v_cmp_ge_f32_e64 s[44:45], v89, v122
	v_cmp_ge_f32_e64 s[22:23], v89, v123
	v_or_b32_e32 v19, 1, v124
	s_andn2_b64 s[22:23], s[22:23], s[44:45]
	s_mov_b64 exec, s[44:45]
	ds_add_rtn_u32 v17, v180, v222
	s_mov_b64 exec, s[22:23]
	ds_add_rtn_u32 v17, v171, v222
	s_mov_b64 exec, -1
	v_cmp_ge_f32_e64 s[20:21], v90, v122
	v_cmp_ge_f32_e64 s[2:3], v90, v123
	v_or_b32_e32 v24, 2, v124
	s_andn2_b64 s[2:3], s[2:3], s[20:21]
	s_mov_b64 exec, s[20:21]
	ds_add_rtn_u32 v23, v180, v222
	s_mov_b64 exec, s[2:3]
	ds_add_rtn_u32 v23, v171, v222
	s_mov_b64 exec, -1
	s_waitcnt lgkmcnt(4)
	v_and_b32_e32 v16, 0xff, v16
	s_mov_b64 exec, s[40:41]
	v_lshl_add_u32 v20, v16, 1, v179
	ds_write_b16 v20, v18
	s_mov_b64 exec, s[42:43]
	s_cbranch_execz .Lm6_nb0
	v_ashrrev_i32_e32 v22, 31, v88
	v_sub_u32_e32 v18, 0x1fff, v18
	v_lshl_add_u32 v20, v16, 2, v169
	v_bitop3_b32 v21, v22, v88, s64 bitop3:0x36
	v_and_or_b32 v21, v21, s65, v18
	ds_write_b32 v20, v21
; __device__ __forceinline__ unsigned sortable(float f) { const unsigned u = __float_as_uint(f); return u ^ ((unsigned)((int)u >> 31) | 0x80000000u); }
; __device__ __forceinline__ int bucketf(float f) { const unsigned u = __float_as_uint(f); const int idx = (int)((u >> 20) & 0x7FFu); const int c = min(max(idx - 816, 128), 255); return c ^ (((int)u >> 31) & 255); }
;     ...
;         const unsigned s0 = (unsigned)(64 * kt + 32 * kb + 4 * hi);
; #pragma unroll
;         for (int r = 0; r < 16; ++r) { const unsigned s = s0 + (unsigned)((r & 3) + 8 * (r >> 2));
;             if (MODE == 5) { __hip_atomic_fetch_add(hist + 64 * bucketf(sc[r]), 1u, __ATOMIC_RELAXED, __HIP_MEMORY_SCOPE_WORKGROUP); continue; }
;             if (MODE == 6) {
;                 if (sc[r] >= t_hi) { const unsigned pos = __hip_atomic_fetch_add(cnt, 1u, __ATOMIC_RELAXED, __HIP_MEMORY_SCOPE_WORKGROUP); sel[pos & 255u] = (unsigned short)s; }
;                 else if (sc[r] >= t_lo) { const unsigned key = (sortable(sc[r]) & 0xFFFFE000u) | (8191u - s);
;                     const unsigned pos = __hip_atomic_fetch_add(ccnt, 1u, __ATOMIC_RELAXED, __HIP_MEMORY_SCOPE_WORKGROUP); cand[pos & (DS_CAP - 1)] = key; }
;                 continue; }
.Lm6_nb0:
	s_mov_b64 exec, -1
	v_cmp_ge_f32_e64 s[40:41], v91, v122
	v_cmp_ge_f32_e64 s[42:43], v91, v123
	v_or_b32_e32 v18, 3, v124
	s_andn2_b64 s[42:43], s[42:43], s[40:41]
	s_mov_b64 exec, s[40:41]
	ds_add_rtn_u32 v16, v180, v222
	s_mov_b64 exec, s[42:43]
	ds_add_rtn_u32 v16, v171, v222
	s_mov_b64 exec, -1
	s_waitcnt lgkmcnt(5)
	v_and_b32_e32 v17, 0xff, v17
	s_mov_b64 exec, s[44:45]
	v_lshl_add_u32 v20, v17, 1, v179
	ds_write_b16 v20, v19
	s_mov_b64 exec, s[22:23]
	s_cbranch_execz .Lm6_nb1
	v_ashrrev_i32_e32 v22, 31, v89
	v_sub_u32_e32 v19, 0x1fff, v19
	v_lshl_add_u32 v20, v17, 2, v169
	v_bitop3_b32 v21, v22, v89, s64 bitop3:0x36
	v_and_or_b32 v21, v21, s65, v19
	ds_write_b32 v20, v21
.Lm6_nb1:
	s_mov_b64 exec, -1
	v_cmp_ge_f32_e64 s[44:45], v92, v122
	v_cmp_ge_f32_e64 s[22:23], v92, v123
	v_or_b32_e32 v19, 8, v124
	s_andn2_b64 s[22:23], s[22:23], s[44:45]
	s_mov_b64 exec, s[44:45]
	ds_add_rtn_u32 v17, v180, v222
	s_mov_b64 exec, s[22:23]
	ds_add_rtn_u32 v17, v171, v222
	s_mov_b64 exec, -1
	s_waitcnt lgkmcnt(6)
	v_and_b32_e32 v23, 0xff, v23
	s_mov_b64 exec, s[20:21]
	v_lshl_add_u32 v20, v23, 1, v179
	ds_write_b16 v20, v24
	s_mov_b64 exec, s[2:3]
	s_cbranch_execz .Lm6_nb2
	v_ashrrev_i32_e32 v22, 31, v90
	v_sub_u32_e32 v24, 0x1fff, v24
	v_lshl_add_u32 v20, v23, 2, v169
	v_bitop3_b32 v21, v22, v90, s64 bitop3:0x36
	v_and_or_b32 v21, v21, s65, v24
	ds_write_b32 v20, v21
.Lm6_nb2:
	s_mov_b64 exec, -1
	v_cmp_ge_f32_e64 s[20:21], v93, v122
	v_cmp_ge_f32_e64 s[2:3], v93, v123
	v_or_b32_e32 v24, 9, v124
	s_andn2_b64 s[2:3], s[2:3], s[20:21]
	s_mov_b64 exec, s[20:21]
	ds_add_rtn_u32 v23, v180, v222
	s_mov_b64 exec, s[2:3]
	ds_add_rtn_u32 v23, v171, v222
	s_mov_b64 exec, -1
	s_waitcnt lgkmcnt(6)
	v_and_b32_e32 v16, 0xff, v16
	s_mov_b64 exec, s[40:41]
	v_lshl_add_u32 v20, v16, 1, v179
	ds_write_b16 v20, v18
	s_mov_b64 exec, s[42:43]
	s_cbranch_execz .Lm6_nb3
	v_ashrrev_i32_e32 v22, 31, v91
	v_sub_u32_e32 v18, 0x1fff, v18
	v_lshl_add_u32 v20, v16, 2, v169
	v_bitop3_b32 v21, v22, v91, s64 bitop3:0x36
	v_and_or_b32 v21, v21, s65, v18
	ds_write_b32 v20, v21
.Lm6_nb3:
	s_mov_b64 exec, -1
	v_cmp_ge_f32_e64 s[40:41], v94, v122
	v_cmp_ge_f32_e64 s[42:43], v94, v123
	v_or_b32_e32 v18, 10, v124
	s_andn2_b64 s[42:43], s[42:43], s[40:41]
	s_mov_b64 exec, s[40:41]
	ds_add_rtn_u32 v16, v180, v222
	s_mov_b64 exec, s[42:43]
	ds_add_rtn_u32 v16, v171, v222
	s_mov_b64 exec, -1
	s_waitcnt lgkmcnt(6)
	v_and_b32_e32 v17, 0xff, v17
	s_mov_b64 exec, s[44:45]
	v_lshl_add_u32 v20, v17, 1, v179
	ds_write_b16 v20, v19
	s_mov_b64 exec, s[22:23]
	s_cbranch_execz .Lm6_nb4
	v_ashrrev_i32_e32 v22, 31, v92
	v_sub_u32_e32 v19, 0x1fff, v19
	v_lshl_add_u32 v20, v17, 2, v169
	v_bitop3_b32 v21, v22, v92, s64 bitop3:0x36
	v_and_or_b32 v21, v21, s65, v19
	ds_write_b32 v20, v21
.Lm6_nb4:
	s_mov_b64 exec, -1
	v_cmp_ge_f32_e64 s[44:45], v95, v122
	v_cmp_ge_f32_e64 s[22:23], v95, v123
	v_or_b32_e32 v19, 11, v124
	s_andn2_b64 s[22:23], s[22:23], s[44:45]
	s_mov_b64 exec, s[44:45]
	ds_add_rtn_u32 v17, v180, v222
	s_mov_b64 exec, s[22:23]
	ds_add_rtn_u32 v17, v171, v222
	s_mov_b64 exec, -1
	s_waitcnt lgkmcnt(6)
	v_and_b32_e32 v23, 0xff, v23
	s_mov_b64 exec, s[20:21]
	v_lshl_add_u32 v20, v23, 1, v179
	ds_write_b16 v20, v24
	s_mov_b64 exec, s[2:3]
	s_cbranch_execz .Lm6_nb5
	v_ashrrev_i32_e32 v22, 31, v93
	v_sub_u32_e32 v24, 0x1fff, v24
	v_lshl_add_u32 v20, v23, 2, v169
	v_bitop3_b32 v21, v22, v93, s64 bitop3:0x36
	v_and_or_b32 v21, v21, s65, v24
	ds_write_b32 v20, v21
.Lm6_nb5:
	s_mov_b64 exec, -1
	v_cmp_ge_f32_e64 s[20:21], v96, v122
	v_cmp_ge_f32_e64 s[2:3], v96, v123
	v_or_b32_e32 v24, 16, v124
	s_andn2_b64 s[2:3], s[2:3], s[20:21]
	s_mov_b64 exec, s[20:21]
	ds_add_rtn_u32 v23, v180, v222
	s_mov_b64 exec, s[2:3]
	ds_add_rtn_u32 v23, v171, v222
	s_mov_b64 exec, -1
	s_waitcnt lgkmcnt(6)
	v_and_b32_e32 v16, 0xff, v16
	s_mov_b64 exec, s[40:41]
	v_lshl_add_u32 v20, v16, 1, v179
	ds_write_b16 v20, v18
	s_mov_b64 exec, s[42:43]
	s_cbranch_execz .Lm6_nb6
	v_ashrrev_i32_e32 v22, 31, v94
	v_sub_u32_e32 v18, 0x1fff, v18
	v_lshl_add_u32 v20, v16, 2, v169
	v_bitop3_b32 v21, v22, v94, s64 bitop3:0x36
	v_and_or_b32 v21, v21, s65, v18
	ds_write_b32 v20, v21
.Lm6_nb6:
	s_mov_b64 exec, -1
	v_cmp_ge_f32_e64 s[40:41], v97, v122
	v_cmp_ge_f32_e64 s[42:43], v97, v123
	v_or_b32_e32 v18, 17, v124
	s_andn2_b64 s[42:43], s[42:43], s[40:41]
	s_mov_b64 exec, s[40:41]
	ds_add_rtn_u32 v16, v180, v222
	s_mov_b64 exec, s[42:43]
	ds_add_rtn_u32 v16, v171, v222
	s_mov_b64 exec, -1
	s_waitcnt lgkmcnt(6)
	v_and_b32_e32 v17, 0xff, v17
	s_mov_b64 exec, s[44:45]
	v_lshl_add_u32 v20, v17, 1, v179
	ds_write_b16 v20, v19
	s_mov_b64 exec, s[22:23]
	s_cbranch_execz .Lm6_nb7
	v_ashrrev_i32_e32 v22, 31, v95
	v_sub_u32_e32 v19, 0x1fff, v19
	v_lshl_add_u32 v20, v17, 2, v169
	v_bitop3_b32 v21, v22, v95, s64 bitop3:0x36
	v_and_or_b32 v21, v21, s65, v19
	ds_write_b32 v20, v21
; __device__ __forceinline__ unsigned sortable(float f) { const unsigned u = __float_as_uint(f); return u ^ ((unsigned)((int)u >> 31) | 0x80000000u); }
; __device__ __forceinline__ int bucketf(float f) { const unsigned u = __float_as_uint(f); const int idx = (int)((u >> 20) & 0x7FFu); const int c = min(max(idx - 816, 128), 255); return c ^ (((int)u >> 31) & 255); }
;     ...
;         const unsigned s0 = (unsigned)(64 * kt + 32 * kb + 4 * hi);
; #pragma unroll
;         for (int r = 0; r < 16; ++r) { const unsigned s = s0 + (unsigned)((r & 3) + 8 * (r >> 2));
;             if (MODE == 5) { __hip_atomic_fetch_add(hist + 64 * bucketf(sc[r]), 1u, __ATOMIC_RELAXED, __HIP_MEMORY_SCOPE_WORKGROUP); continue; }
;             if (MODE == 6) {
;                 if (sc[r] >= t_hi) { const unsigned pos = __hip_atomic_fetch_add(cnt, 1u, __ATOMIC_RELAXED, __HIP_MEMORY_SCOPE_WORKGROUP); sel[pos & 255u] = (unsigned short)s; }
;                 else if (sc[r] >= t_lo) { const unsigned key = (sortable(sc[r]) & 0xFFFFE000u) | (8191u - s);
;                     const unsigned pos = __hip_atomic_fetch_add(ccnt, 1u, __ATOMIC_RELAXED, __HIP_MEMORY_SCOPE_WORKGROUP); cand[pos & (DS_CAP - 1)] = key; }
;                 continue; }
.Lm6_nb7:
	s_mov_b64 exec, -1
	v_cmp_ge_f32_e64 s[44:45], v98, v122
	v_cmp_ge_f32_e64 s[22:23], v98, v123
	v_or_b32_e32 v19, 18, v124
	s_andn2_b64 s[22:23], s[22:23], s[44:45]
	s_mov_b64 exec, s[44:45]
	ds_add_rtn_u32 v17, v180, v222
	s_mov_b64 exec, s[22:23]
	ds_add_rtn_u32 v17, v171, v222
	s_mov_b64 exec, -1
	s_waitcnt lgkmcnt(6)
	v_and_b32_e32 v23, 0xff, v23
	s_mov_b64 exec, s[20:21]
	v_lshl_add_u32 v20, v23, 1, v179
	ds_write_b16 v20, v24
	s_mov_b64 exec, s[2:3]
	s_cbranch_execz .Lm6_nb8
	v_ashrrev_i32_e32 v22, 31, v96
	v_sub_u32_e32 v24, 0x1fff, v24
	v_lshl_add_u32 v20, v23, 2, v169
	v_bitop3_b32 v21, v22, v96, s64 bitop3:0x36
	v_and_or_b32 v21, v21, s65, v24
	ds_write_b32 v20, v21
.Lm6_nb8:
	s_mov_b64 exec, -1
	v_cmp_ge_f32_e64 s[20:21], v99, v122
	v_cmp_ge_f32_e64 s[2:3], v99, v123
	v_or_b32_e32 v24, 19, v124
	s_andn2_b64 s[2:3], s[2:3], s[20:21]
	s_mov_b64 exec, s[20:21]
	ds_add_rtn_u32 v23, v180, v222
	s_mov_b64 exec, s[2:3]
	ds_add_rtn_u32 v23, v171, v222
	s_mov_b64 exec, -1
	s_waitcnt lgkmcnt(6)
	v_and_b32_e32 v16, 0xff, v16
	s_mov_b64 exec, s[40:41]
	v_lshl_add_u32 v20, v16, 1, v179
	ds_write_b16 v20, v18
	s_mov_b64 exec, s[42:43]
	s_cbranch_execz .Lm6_nb9
	v_ashrrev_i32_e32 v22, 31, v97
	v_sub_u32_e32 v18, 0x1fff, v18
	v_lshl_add_u32 v20, v16, 2, v169
	v_bitop3_b32 v21, v22, v97, s64 bitop3:0x36
	v_and_or_b32 v21, v21, s65, v18
	ds_write_b32 v20, v21
.Lm6_nb9:
	s_mov_b64 exec, -1
	v_cmp_ge_f32_e64 s[40:41], v100, v122
	v_cmp_ge_f32_e64 s[42:43], v100, v123
	v_or_b32_e32 v18, 24, v124
	s_andn2_b64 s[42:43], s[42:43], s[40:41]
	s_mov_b64 exec, s[40:41]
	ds_add_rtn_u32 v16, v180, v222
	s_mov_b64 exec, s[42:43]
	ds_add_rtn_u32 v16, v171, v222
	s_mov_b64 exec, -1
	s_waitcnt lgkmcnt(6)
	v_and_b32_e32 v17, 0xff, v17
	s_mov_b64 exec, s[44:45]
	v_lshl_add_u32 v20, v17, 1, v179
	ds_write_b16 v20, v19
	s_mov_b64 exec, s[22:23]
	s_cbranch_execz .Lm6_nb10
	v_ashrrev_i32_e32 v22, 31, v98
	v_sub_u32_e32 v19, 0x1fff, v19
	v_lshl_add_u32 v20, v17, 2, v169
	v_bitop3_b32 v21, v22, v98, s64 bitop3:0x36
	v_and_or_b32 v21, v21, s65, v19
	ds_write_b32 v20, v21
.Lm6_nb10:
	s_mov_b64 exec, -1
	v_cmp_ge_f32_e64 s[44:45], v101, v122
	v_cmp_ge_f32_e64 s[22:23], v101, v123
	v_or_b32_e32 v19, 25, v124
	s_andn2_b64 s[22:23], s[22:23], s[44:45]
	s_mov_b64 exec, s[44:45]
	ds_add_rtn_u32 v17, v180, v222
	s_mov_b64 exec, s[22:23]
	ds_add_rtn_u32 v17, v171, v222
	s_mov_b64 exec, -1
	s_waitcnt lgkmcnt(6)
	v_and_b32_e32 v23, 0xff, v23
	s_mov_b64 exec, s[20:21]
	v_lshl_add_u32 v20, v23, 1, v179
	ds_write_b16 v20, v24
	s_mov_b64 exec, s[2:3]
	s_cbranch_execz .Lm6_nb11
	v_ashrrev_i32_e32 v22, 31, v99
	v_sub_u32_e32 v24, 0x1fff, v24
	v_lshl_add_u32 v20, v23, 2, v169
	v_bitop3_b32 v21, v22, v99, s64 bitop3:0x36
	v_and_or_b32 v21, v21, s65, v24
	ds_write_b32 v20, v21
.Lm6_nb11:
	s_mov_b64 exec, -1
	v_cmp_ge_f32_e64 s[20:21], v102, v122
	v_cmp_ge_f32_e64 s[2:3], v102, v123
	v_or_b32_e32 v24, 26, v124
	s_andn2_b64 s[2:3], s[2:3], s[20:21]
	s_mov_b64 exec, s[20:21]
	ds_add_rtn_u32 v23, v180, v222
	s_mov_b64 exec, s[2:3]
	ds_add_rtn_u32 v23, v171, v222
	s_mov_b64 exec, -1
	s_waitcnt lgkmcnt(6)
	v_and_b32_e32 v16, 0xff, v16
	s_mov_b64 exec, s[40:41]
	v_lshl_add_u32 v20, v16, 1, v179
	ds_write_b16 v20, v18
	s_mov_b64 exec, s[42:43]
	s_cbranch_execz .Lm6_nb12
	v_ashrrev_i32_e32 v22, 31, v100
	v_sub_u32_e32 v18, 0x1fff, v18
	v_lshl_add_u32 v20, v16, 2, v169
	v_bitop3_b32 v21, v22, v100, s64 bitop3:0x36
	v_and_or_b32 v21, v21, s65, v18
	ds_write_b32 v20, v21
.Lm6_nb12:
	s_mov_b64 exec, -1
	v_cmp_ge_f32_e64 s[40:41], v103, v122
	v_cmp_ge_f32_e64 s[42:43], v103, v123
	v_or_b32_e32 v18, 27, v124
	s_andn2_b64 s[42:43], s[42:43], s[40:41]
	s_mov_b64 exec, s[40:41]
	ds_add_rtn_u32 v16, v180, v222
	s_mov_b64 exec, s[42:43]
	ds_add_rtn_u32 v16, v171, v222
	s_mov_b64 exec, -1
	s_waitcnt lgkmcnt(6)
	v_and_b32_e32 v17, 0xff, v17
	s_mov_b64 exec, s[44:45]
	v_lshl_add_u32 v20, v17, 1, v179
	ds_write_b16 v20, v19
	s_mov_b64 exec, s[22:23]
	s_cbranch_execz .Lm6_nb13
	v_ashrrev_i32_e32 v22, 31, v101
	v_sub_u32_e32 v19, 0x1fff, v19
	v_lshl_add_u32 v20, v17, 2, v169
	v_bitop3_b32 v21, v22, v101, s64 bitop3:0x36
	v_and_or_b32 v21, v21, s65, v19
	ds_write_b32 v20, v21
.Lm6_nb13:
	s_mov_b64 exec, -1
	s_waitcnt lgkmcnt(4)
	v_and_b32_e32 v23, 0xff, v23
	s_mov_b64 exec, s[20:21]
	v_lshl_add_u32 v20, v23, 1, v179
	ds_write_b16 v20, v24
	s_mov_b64 exec, s[2:3]
	s_cbranch_execz .Lm6_nb14
	v_ashrrev_i32_e32 v22, 31, v102
	v_sub_u32_e32 v24, 0x1fff, v24
	v_lshl_add_u32 v20, v23, 2, v169
	v_bitop3_b32 v21, v22, v102, s64 bitop3:0x36
	v_and_or_b32 v21, v21, s65, v24
	ds_write_b32 v20, v21
.Lm6_nb14:
	s_mov_b64 exec, -1
	s_waitcnt lgkmcnt(2)
	v_and_b32_e32 v16, 0xff, v16
	s_mov_b64 exec, s[40:41]
	v_lshl_add_u32 v20, v16, 1, v179
	ds_write_b16 v20, v18
	s_mov_b64 exec, s[42:43]
	s_cbranch_execz .Lm6_nb15
	v_ashrrev_i32_e32 v22, 31, v103
	v_sub_u32_e32 v18, 0x1fff, v18
	v_lshl_add_u32 v20, v16, 2, v169
	v_bitop3_b32 v21, v22, v103, s64 bitop3:0x36
	v_and_or_b32 v21, v21, s65, v18
	ds_write_b32 v20, v21
